# MLA loop: every v_mfma placed at an address = 0 mod 8 (s_nop 0 pad in front of the ones the assembler put at 4 mod 8)
# speedup vs baseline: 1.0061x; 1.0061x over previous
.Lmla_loop:
	ds_read_b128 v[230:233], v193 offset:24576
	ds_read_b128 v[234:237], v186 offset:24576
	ds_read_b128 v[238:241], v187 offset:24576
	ds_read_b128 v[242:245], v188 offset:24576
	s_cmp_lt_u32 s58, s18
	s_cselect_b32 s0, 0, s18
	s_cselect_b32 s1, s6, s13
	s_lshl_b32 s0, s0, 6
	s_sub_i32 s0, s1, s0
	s_add_i32 s0, s51, s0
	s_ashr_i32 s1, s0, 31
	s_lshl_b64 s[10:11], s[0:1], 12
	s_add_u32 s16, s20, s10
	s_addc_u32 s17, s21, s11
	v_exp_f32_e32 v64, v64
	v_exp_f32_e32 v65, v65
	v_add_f32_e32 v212, v64, v212
	v_exp_f32_e32 v66, v66
	v_add_f32_e32 v212, v65, v212
	v_exp_f32_e32 v67, v67
	s_waitcnt lgkmcnt(3)
	s_nop 0
	v_mfma_f32_32x32x16_bf16 v[80:95], v[230:233], v[124:127], 0
	ds_read_b128 v[230:233], v189 offset:24576
	s_cmp_eq_u32 s58, 2
	s_cbranch_scc1 .Lmla_skipv0_o
	s_mov_b32 m0, s54
	v_lshl_add_u64 v[254:255], v[164:165], 1, s[100:101]
	global_load_lds_dwordx4 v[254:255], off

.Lmla_skipv1_o:
	v_add_f32_e32 v212, v68, v212
	v_exp_f32_e32 v70, v70
	v_add_f32_e32 v212, v69, v212
	v_exp_f32_e32 v71, v71
	s_waitcnt lgkmcnt(3)
	v_mfma_f32_32x32x16_bf16 v[80:95], v[238:241], v[116:119], v[80:95]
	ds_read_b128 v[238:241], v191 offset:24576
	v_add_f32_e32 v212, v70, v212
	v_exp_f32_e32 v72, v72
	v_add_f32_e32 v212, v71, v212
	v_exp_f32_e32 v73, v73
	s_waitcnt lgkmcnt(3)
	s_nop 0
	v_mfma_f32_32x32x16_bf16 v[80:95], v[242:245], v[112:115], v[80:95]
	ds_read_b128 v[242:245], v192 offset:24576
	s_mov_b32 m0, s23
	v_lshl_add_u64 v[254:255], v[160:161], 1, s[16:17]
	global_load_lds_dwordx4 v[254:255], off
	v_add_f32_e32 v212, v72, v212
	v_exp_f32_e32 v74, v74
	v_add_f32_e32 v212, v73, v212
	v_exp_f32_e32 v75, v75
	s_waitcnt lgkmcnt(3)
	v_mfma_f32_32x32x16_bf16 v[80:95], v[230:233], v[108:111], v[80:95]
	ds_read_b128 v[230:233], v203 offset:24576
	v_add_f32_e32 v212, v74, v212
	v_exp_f32_e32 v76, v76
	v_add_f32_e32 v212, v75, v212
	v_exp_f32_e32 v77, v77
	s_waitcnt lgkmcnt(3)
	s_nop 0
	v_mfma_f32_32x32x16_bf16 v[80:95], v[234:237], v[104:107], v[80:95]
	ds_read_b128 v[234:237], v204 offset:24576
	s_mov_b32 m0, s7
	v_lshl_add_u64 v[254:255], v[162:163], 1, s[16:17]
	global_load_lds_dwordx4 v[254:255], off
	v_add_f32_e32 v212, v76, v212
	v_exp_f32_e32 v78, v78
	v_add_f32_e32 v212, v77, v212
	v_exp_f32_e32 v79, v79
	s_waitcnt lgkmcnt(3)
	v_mfma_f32_32x32x16_bf16 v[80:95], v[238:241], v[100:103], v[80:95]
	ds_read_b128 v[238:241], v205 offset:24576
	v_add_f32_e32 v212, v78, v212
	v_add_f32_e32 v212, v79, v212
	v_mov_b32_e32 v213, v212
	s_waitcnt lgkmcnt(3)
	v_mfma_f32_32x32x16_bf16 v[80:95], v[242:245], v[96:99], v[80:95]
	ds_read_b128 v[242:245], v206 offset:24576
	s_mov_b32 m0, s30
	v_mad_i64_i32 v[254:255], s[0:1], s0, v180, v[168:169]
	global_load_lds_dwordx4 v[254:255], off
	s_add_u32 s100, s16, 0x100
	s_addc_u32 s101, s17, 0
	v_cvt_pk_bf16_f32 v152, v64, v65
	v_cvt_pk_bf16_f32 v153, v66, v67
	v_cvt_pk_bf16_f32 v154, v68, v69
	s_waitcnt lgkmcnt(3)
	s_nop 0
	v_mfma_f32_32x32x16_bf16 v[80:95], v[230:233], v[128:131], v[80:95]
	ds_read_b128 v[230:233], v193 offset:32768
	v_cvt_pk_bf16_f32 v155, v70, v71
	v_cvt_pk_bf16_f32 v156, v72, v73
	v_cvt_pk_bf16_f32 v157, v74, v75
	s_waitcnt lgkmcnt(3)
	s_nop 0
	v_mfma_f32_32x32x16_bf16 v[80:95], v[234:237], v[132:135], v[80:95]
	ds_read_b128 v[234:237], v186 offset:32768
	v_cvt_pk_bf16_f32 v158, v76, v77
	v_cvt_pk_bf16_f32 v159, v78, v79
	v_permlane32_swap_b32_e32 v212, v213
	s_waitcnt lgkmcnt(3)
	v_mfma_f32_32x32x16_bf16 v[80:95], v[238:241], v[136:139], v[80:95]
	ds_read_b128 v[238:241], v187 offset:32768
	v_add_f32_e32 v252, v212, v213
	v_fma_f32 v183, v207, v183, v252
	v_permlane32_swap_b32_e32 v152, v154
	s_waitcnt lgkmcnt(3)
	s_nop 0
	v_mfma_f32_32x32x16_bf16 v[80:95], v[242:245], v[140:143], v[80:95]
	ds_read_b128 v[242:245], v188 offset:32768
	v_permlane32_swap_b32_e32 v153, v155
	v_permlane32_swap_b32_e32 v156, v158
	v_permlane32_swap_b32_e32 v157, v159
	s_waitcnt lgkmcnt(3)
	v_mfma_f32_32x32x16_bf16 v[64:79], v[230:233], v[124:127], 0
	ds_read_b128 v[230:233], v189 offset:32768
	s_waitcnt lgkmcnt(3)
	s_nop 0
	v_mfma_f32_32x32x16_bf16 v[64:79], v[234:237], v[120:123], v[64:79]
	ds_read_b128 v[234:237], v190 offset:32768
	s_waitcnt lgkmcnt(3)
	s_nop 0
	v_mfma_f32_32x32x16_bf16 v[64:79], v[238:241], v[116:119], v[64:79]
	ds_read_b128 v[238:241], v191 offset:32768
	s_waitcnt lgkmcnt(3)
	s_nop 0
	v_mfma_f32_32x32x16_bf16 v[64:79], v[242:245], v[112:115], v[64:79]
	ds_read_b128 v[242:245], v192 offset:32768
	s_waitcnt lgkmcnt(3)
	s_nop 0
	v_mfma_f32_32x32x16_bf16 v[64:79], v[230:233], v[108:111], v[64:79]
	ds_read_b128 v[230:233], v203 offset:28672
	s_waitcnt lgkmcnt(3)
	s_nop 0
	v_mfma_f32_32x32x16_bf16 v[64:79], v[234:237], v[104:107], v[64:79]
	ds_read_b128 v[234:237], v204 offset:28672
	s_waitcnt lgkmcnt(3)
	s_nop 0
	v_mfma_f32_32x32x16_bf16 v[64:79], v[238:241], v[100:103], v[64:79]
	ds_read_b128 v[238:241], v205 offset:28672
	v_max_f32_e32 v249, v80, v81
	v_max3_f32 v249, v249, v82, v83
	s_waitcnt lgkmcnt(3)
	v_mfma_f32_32x32x16_bf16 v[64:79], v[242:245], v[96:99], v[64:79]
	ds_read_b128 v[242:245], v206 offset:28672
	v_max3_f32 v249, v249, v84, v85
	v_max3_f32 v249, v249, v86, v87
	s_waitcnt lgkmcnt(3)
	s_nop 0
	v_mfma_f32_32x32x16_bf16 v[64:79], v[230:233], v[128:131], v[64:79]
	ds_read_b64_tr_b16 v[214:215], v185
	ds_read_b64_tr_b16 v[216:217], v185 offset:2048
	v_max3_f32 v249, v249, v88, v89
	v_max3_f32 v249, v249, v90, v91
	s_waitcnt lgkmcnt(4)
	s_nop 0
	v_mfma_f32_32x32x16_bf16 v[64:79], v[234:237], v[132:135], v[64:79]
	ds_read_b64_tr_b16 v[218:219], v185 offset:4096
	ds_read_b64_tr_b16 v[220:221], v185 offset:6144
	v_max3_f32 v249, v249, v92, v93
	v_max3_f32 v249, v249, v94, v95
	s_waitcnt lgkmcnt(5)
	s_nop 0
	v_mfma_f32_32x32x16_bf16 v[64:79], v[238:241], v[136:139], v[64:79]
	ds_read_b64_tr_b16 v[222:223], v185 offset:8192
	ds_read_b64_tr_b16 v[224:225], v185 offset:10240
	s_waitcnt lgkmcnt(6)
	s_nop 0
	v_mfma_f32_32x32x16_bf16 v[64:79], v[242:245], v[140:143], v[64:79]
	ds_read_b64_tr_b16 v[226:227], v185 offset:12288
	ds_read_b64_tr_b16 v[228:229], v185 offset:14336
	s_waitcnt lgkmcnt(6)
	s_nop 0
	v_mfma_f32_32x32x16_bf16 v[0:15], v[214:217], v[144:147], v[0:15]
	ds_read_b64_tr_b16 v[214:215], v185 offset:512
	ds_read_b64_tr_b16 v[216:217], v185 offset:2560
	s_waitcnt lgkmcnt(6)
	s_nop 0
	v_mfma_f32_32x32x16_bf16 v[0:15], v[218:221], v[148:151], v[0:15]
	ds_read_b64_tr_b16 v[218:219], v185 offset:4608
	ds_read_b64_tr_b16 v[220:221], v185 offset:6656
	s_waitcnt lgkmcnt(6)
	s_nop 0
	v_mfma_f32_32x32x16_bf16 v[0:15], v[222:225], v[152:155], v[0:15]
	ds_read_b64_tr_b16 v[222:223], v185 offset:8704
	ds_read_b64_tr_b16 v[224:225], v185 offset:10752
	s_waitcnt lgkmcnt(6)
	s_nop 0
	v_mfma_f32_32x32x16_bf16 v[0:15], v[226:229], v[156:159], v[0:15]
	ds_read_b64_tr_b16 v[226:227], v185 offset:12800
	ds_read_b64_tr_b16 v[228:229], v185 offset:14848
	s_waitcnt lgkmcnt(6)
	s_nop 0
	v_mfma_f32_32x32x16_bf16 v[48:63], v[214:217], v[144:147], v[48:63]
	ds_read_b64_tr_b16 v[214:215], v185 offset:1024
	ds_read_b64_tr_b16 v[216:217], v185 offset:3072
	v_max3_f32 v249, v249, v64, v65
	v_max3_f32 v249, v249, v66, v67
	v_max3_f32 v249, v249, v68, v69
	v_max3_f32 v249, v249, v70, v71
	v_max3_f32 v249, v249, v72, v73
	v_max3_f32 v249, v249, v74, v75
	v_max3_f32 v249, v249, v76, v77
	v_max3_f32 v249, v249, v78, v79
	s_waitcnt lgkmcnt(6)
	s_nop 0
	v_mfma_f32_32x32x16_bf16 v[48:63], v[218:221], v[148:151], v[48:63]
	ds_read_b64_tr_b16 v[218:219], v185 offset:5120
	ds_read_b64_tr_b16 v[220:221], v185 offset:7168
	v_mov_b32_e32 v250, v249
	s_nop 1
	v_permlane32_swap_b32_e32 v249, v250
	v_max_f32_e32 v249, v249, v250
	v_sub_f32_e32 v250, v249, v208
	v_cmp_ge_f32_e32 vcc, s40, v250
	v_max_f32_e32 v249, v208, v249
	v_sub_f32_e32 v250, v208, v249
	s_waitcnt lgkmcnt(6)
	s_nop 0
	v_mfma_f32_32x32x16_bf16 v[48:63], v[222:225], v[152:155], v[48:63]
	ds_read_b64_tr_b16 v[222:223], v185 offset:9216
	ds_read_b64_tr_b16 v[224:225], v185 offset:11264
	v_mul_f32_e32 v250, 0x3dd53b94, v250
	v_exp_f32_e32 v250, v250
	s_cmp_eq_u64 vcc, exec
	s_cselect_b64 s[10:11], -1, 0
	v_cndmask_b32_e64 v207, v250, 1.0, s[10:11]
	v_cndmask_b32_e64 v208, v249, v208, s[10:11]
	v_mul_f32_e32 v251, 0xbdd53b94, v208
	v_fmamk_f32 v80, v80, 0x3dd53b94, v251
	s_waitcnt lgkmcnt(6)
	v_mfma_f32_32x32x16_bf16 v[48:63], v[226:229], v[156:159], v[48:63]
	ds_read_b64_tr_b16 v[226:227], v185 offset:13312
	ds_read_b64_tr_b16 v[228:229], v185 offset:15360
	v_fmamk_f32 v81, v81, 0x3dd53b94, v251
	v_fmamk_f32 v82, v82, 0x3dd53b94, v251
	v_fmamk_f32 v83, v83, 0x3dd53b94, v251
	v_fmamk_f32 v84, v84, 0x3dd53b94, v251
	v_fmamk_f32 v85, v85, 0x3dd53b94, v251
	v_fmamk_f32 v86, v86, 0x3dd53b94, v251
	v_fmamk_f32 v87, v87, 0x3dd53b94, v251
	s_waitcnt lgkmcnt(6)
	s_nop 0
	v_mfma_f32_32x32x16_bf16 v[32:47], v[214:217], v[144:147], v[32:47]
	ds_read_b64_tr_b16 v[214:215], v185 offset:1536
	ds_read_b64_tr_b16 v[216:217], v185 offset:3584
	v_fmamk_f32 v88, v88, 0x3dd53b94, v251
	v_fmamk_f32 v89, v89, 0x3dd53b94, v251
	v_fmamk_f32 v90, v90, 0x3dd53b94, v251
	v_fmamk_f32 v91, v91, 0x3dd53b94, v251
	v_fmamk_f32 v92, v92, 0x3dd53b94, v251
	v_fmamk_f32 v93, v93, 0x3dd53b94, v251
	v_fmamk_f32 v94, v94, 0x3dd53b94, v251
	s_waitcnt lgkmcnt(6)
	s_nop 0
	v_mfma_f32_32x32x16_bf16 v[32:47], v[218:221], v[148:151], v[32:47]
	ds_read_b64_tr_b16 v[218:219], v185 offset:5632
	ds_read_b64_tr_b16 v[220:221], v185 offset:7680
	v_fmamk_f32 v95, v95, 0x3dd53b94, v251
	v_exp_f32_e32 v80, v80
	v_fmamk_f32 v64, v64, 0x3dd53b94, v251
	v_exp_f32_e32 v81, v81
	v_fmamk_f32 v65, v65, 0x3dd53b94, v251
	v_add_f32_e32 v212, 0, v80
	v_exp_f32_e32 v82, v82
	s_waitcnt lgkmcnt(6)
	s_nop 0
	v_mfma_f32_32x32x16_bf16 v[32:47], v[222:225], v[152:155], v[32:47]
	ds_read_b64_tr_b16 v[222:223], v185 offset:9728
	ds_read_b64_tr_b16 v[224:225], v185 offset:11776
	v_fmamk_f32 v66, v66, 0x3dd53b94, v251
	v_add_f32_e32 v212, v81, v212
	v_exp_f32_e32 v83, v83
	v_fmamk_f32 v67, v67, 0x3dd53b94, v251
	v_add_f32_e32 v212, v82, v212
	v_exp_f32_e32 v84, v84
	v_fmamk_f32 v68, v68, 0x3dd53b94, v251
	s_waitcnt lgkmcnt(6)
	s_nop 0
	v_mfma_f32_32x32x16_bf16 v[32:47], v[226:229], v[156:159], v[32:47]
	ds_read_b64_tr_b16 v[226:227], v185 offset:13824
	ds_read_b64_tr_b16 v[228:229], v185 offset:15872
	v_add_f32_e32 v212, v83, v212
	v_exp_f32_e32 v85, v85
	v_fmamk_f32 v69, v69, 0x3dd53b94, v251
	v_add_f32_e32 v212, v84, v212
	v_exp_f32_e32 v86, v86
	v_fmamk_f32 v70, v70, 0x3dd53b94, v251
	v_add_f32_e32 v212, v85, v212
	s_waitcnt lgkmcnt(6)
	v_mfma_f32_32x32x16_bf16 v[16:31], v[214:217], v[144:147], v[16:31]
	v_exp_f32_e32 v87, v87
	v_fmamk_f32 v71, v71, 0x3dd53b94, v251
	v_add_f32_e32 v212, v86, v212
	v_exp_f32_e32 v88, v88
	v_fmamk_f32 v72, v72, 0x3dd53b94, v251
	v_add_f32_e32 v212, v87, v212
	v_exp_f32_e32 v89, v89
	s_waitcnt lgkmcnt(4)
	v_mfma_f32_32x32x16_bf16 v[16:31], v[218:221], v[148:151], v[16:31]
	v_fmamk_f32 v73, v73, 0x3dd53b94, v251
	v_add_f32_e32 v212, v88, v212
	v_exp_f32_e32 v90, v90
	v_fmamk_f32 v74, v74, 0x3dd53b94, v251
	v_add_f32_e32 v212, v89, v212
	v_exp_f32_e32 v91, v91
	v_fmamk_f32 v75, v75, 0x3dd53b94, v251
	s_waitcnt lgkmcnt(2)
	s_nop 0
	v_mfma_f32_32x32x16_bf16 v[16:31], v[222:225], v[152:155], v[16:31]
	v_add_f32_e32 v212, v90, v212
	v_exp_f32_e32 v92, v92
	v_fmamk_f32 v76, v76, 0x3dd53b94, v251
	v_add_f32_e32 v212, v91, v212
	v_exp_f32_e32 v93, v93
	v_fmamk_f32 v77, v77, 0x3dd53b94, v251
	v_add_f32_e32 v212, v92, v212
	s_waitcnt lgkmcnt(0)
	v_mfma_f32_32x32x16_bf16 v[16:31], v[226:229], v[156:159], v[16:31]
	v_exp_f32_e32 v94, v94
	v_fmamk_f32 v78, v78, 0x3dd53b94, v251
	v_add_f32_e32 v212, v93, v212
	v_exp_f32_e32 v95, v95
	v_fmamk_f32 v79, v79, 0x3dd53b94, v251
	v_add_f32_e32 v212, v94, v212
	v_add_f32_e32 v212, v95, v212
	v_cvt_pk_bf16_f32 v144, v80, v81
	v_cvt_pk_bf16_f32 v145, v82, v83
	v_cvt_pk_bf16_f32 v146, v84, v85
	v_cvt_pk_bf16_f32 v147, v86, v87
	v_cvt_pk_bf16_f32 v148, v88, v89
	v_cvt_pk_bf16_f32 v149, v90, v91
	v_cvt_pk_bf16_f32 v150, v92, v93
	v_cvt_pk_bf16_f32 v151, v94, v95
	v_permlane32_swap_b32_e32 v144, v146
	v_permlane32_swap_b32_e32 v145, v147
	v_permlane32_swap_b32_e32 v148, v150
	v_permlane32_swap_b32_e32 v149, v151
	v_cmp_gt_f32_e32 vcc, 1.0, v207
	s_cbranch_vccz .Lmla_noresc_o
	v_mul_f32_e32 v0, v207, v0
	v_mul_f32_e32 v1, v207, v1
	v_mul_f32_e32 v2, v207, v2
	v_mul_f32_e32 v3, v207, v3
	v_mul_f32_e32 v4, v207, v4
	v_mul_f32_e32 v5, v207, v5
	v_mul_f32_e32 v6, v207, v6
	v_mul_f32_e32 v7, v207, v7
	v_mul_f32_e32 v8, v207, v8
	v_mul_f32_e32 v9, v207, v9
	v_mul_f32_e32 v10, v207, v10
	v_mul_f32_e32 v11, v207, v11
	v_mul_f32_e32 v12, v207, v12
	v_mul_f32_e32 v13, v207, v13
	v_mul_f32_e32 v14, v207, v14
	v_mul_f32_e32 v15, v207, v15
	v_mul_f32_e32 v48, v207, v48
	v_mul_f32_e32 v49, v207, v49
	v_mul_f32_e32 v50, v207, v50
	v_mul_f32_e32 v51, v207, v51
	v_mul_f32_e32 v52, v207, v52
	v_mul_f32_e32 v53, v207, v53
	v_mul_f32_e32 v54, v207, v54
	v_mul_f32_e32 v55, v207, v55
	v_mul_f32_e32 v56, v207, v56
	v_mul_f32_e32 v57, v207, v57
	v_mul_f32_e32 v58, v207, v58
	v_mul_f32_e32 v59, v207, v59
	v_mul_f32_e32 v60, v207, v60
	v_mul_f32_e32 v61, v207, v61
	v_mul_f32_e32 v62, v207, v62
	v_mul_f32_e32 v63, v207, v63
	v_mul_f32_e32 v32, v207, v32
	v_mul_f32_e32 v33, v207, v33
	v_mul_f32_e32 v34, v207, v34
	v_mul_f32_e32 v35, v207, v35
	v_mul_f32_e32 v36, v207, v36
	v_mul_f32_e32 v37, v207, v37
	v_mul_f32_e32 v38, v207, v38
	v_mul_f32_e32 v39, v207, v39
	v_mul_f32_e32 v40, v207, v40
	v_mul_f32_e32 v41, v207, v41
	v_mul_f32_e32 v42, v207, v42
	v_mul_f32_e32 v43, v207, v43
	v_mul_f32_e32 v44, v207, v44
	v_mul_f32_e32 v45, v207, v45
	v_mul_f32_e32 v46, v207, v46
	v_mul_f32_e32 v47, v207, v47
	v_mul_f32_e32 v16, v207, v16
	v_mul_f32_e32 v17, v207, v17
	v_mul_f32_e32 v18, v207, v18
	v_mul_f32_e32 v19, v207, v19
	v_mul_f32_e32 v20, v207, v20
	v_mul_f32_e32 v21, v207, v21
	v_mul_f32_e32 v22, v207, v22
	v_mul_f32_e32 v23, v207, v23
	v_mul_f32_e32 v24, v207, v24
	v_mul_f32_e32 v25, v207, v25
	v_mul_f32_e32 v26, v207, v26
	v_mul_f32_e32 v27, v207, v27
	v_mul_f32_e32 v28, v207, v28
	v_mul_f32_e32 v29, v207, v29
	v_mul_f32_e32 v30, v207, v30
	v_mul_f32_e32 v31, v207, v31
.Lmla_noresc_o:
	s_add_i32 s58, s58, 1
	s_waitcnt vmcnt(0) lgkmcnt(0)
	s_barrier
	ds_read_b128 v[230:233], v193
	ds_read_b128 v[234:237], v186
	ds_read_b128 v[238:241], v187
	ds_read_b128 v[242:245], v188
	s_cmp_lt_u32 s58, s18
	s_cselect_b32 s0, 0, s18
	s_cselect_b32 s1, s6, s13
	s_lshl_b32 s0, s0, 6
	s_sub_i32 s0, s1, s0
	s_add_i32 s0, s51, s0
	s_add_i32 s0, s0, 64
	s_ashr_i32 s1, s0, 31
	s_lshl_b64 s[10:11], s[0:1], 12
	s_add_u32 s16, s20, s10
	s_addc_u32 s17, s21, s11
	v_exp_f32_e32 v64, v64
	v_exp_f32_e32 v65, v65
	v_add_f32_e32 v212, v64, v212
	v_exp_f32_e32 v66, v66
	v_add_f32_e32 v212, v65, v212
	v_exp_f32_e32 v67, v67
	s_waitcnt lgkmcnt(3)
	v_mfma_f32_32x32x16_bf16 v[80:95], v[230:233], v[124:127], 0
	ds_read_b128 v[230:233], v189
	s_mov_b32 m0, s22
	v_lshl_add_u64 v[254:255], v[164:165], 1, s[100:101]
	global_load_lds_dwordx4 v[254:255], off
	v_add_f32_e32 v212, v66, v212
	v_exp_f32_e32 v68, v68
	v_add_f32_e32 v212, v67, v212
	v_exp_f32_e32 v69, v69
	s_waitcnt lgkmcnt(3)
	v_mfma_f32_32x32x16_bf16 v[80:95], v[234:237], v[120:123], v[80:95]
	ds_read_b128 v[234:237], v190
	s_mov_b32 m0, s31
	v_lshl_add_u64 v[254:255], v[166:167], 1, s[100:101]
	global_load_lds_dwordx4 v[254:255], off
	v_add_f32_e32 v212, v68, v212
	v_exp_f32_e32 v70, v70
	v_add_f32_e32 v212, v69, v212
	v_exp_f32_e32 v71, v71
	s_waitcnt lgkmcnt(3)
	v_mfma_f32_32x32x16_bf16 v[80:95], v[238:241], v[116:119], v[80:95]
	ds_read_b128 v[238:241], v191
	v_add_f32_e32 v212, v70, v212
	v_exp_f32_e32 v72, v72
	v_add_f32_e32 v212, v71, v212
	v_exp_f32_e32 v73, v73
	s_waitcnt lgkmcnt(3)
	s_nop 0
	v_mfma_f32_32x32x16_bf16 v[80:95], v[242:245], v[112:115], v[80:95]
	ds_read_b128 v[242:245], v192
	s_mov_b32 m0, s44
	v_lshl_add_u64 v[254:255], v[160:161], 1, s[16:17]
	global_load_lds_dwordx4 v[254:255], off
	v_add_f32_e32 v212, v72, v212
	v_exp_f32_e32 v74, v74
	v_add_f32_e32 v212, v73, v212
	v_exp_f32_e32 v75, v75
	s_waitcnt lgkmcnt(3)
	v_mfma_f32_32x32x16_bf16 v[80:95], v[230:233], v[108:111], v[80:95]
	ds_read_b128 v[230:233], v203
	v_add_f32_e32 v212, v74, v212
	v_exp_f32_e32 v76, v76
	v_add_f32_e32 v212, v75, v212
	v_exp_f32_e32 v77, v77
	s_waitcnt lgkmcnt(3)
	s_nop 0
	v_mfma_f32_32x32x16_bf16 v[80:95], v[234:237], v[104:107], v[80:95]
	ds_read_b128 v[234:237], v204
	s_mov_b32 m0, s45
	v_lshl_add_u64 v[254:255], v[162:163], 1, s[16:17]
	global_load_lds_dwordx4 v[254:255], off
	v_add_f32_e32 v212, v76, v212
	v_exp_f32_e32 v78, v78
	v_add_f32_e32 v212, v77, v212
	v_exp_f32_e32 v79, v79
	s_waitcnt lgkmcnt(3)
	v_mfma_f32_32x32x16_bf16 v[80:95], v[238:241], v[100:103], v[80:95]
	ds_read_b128 v[238:241], v205
	v_add_f32_e32 v212, v78, v212
	v_add_f32_e32 v212, v79, v212
	v_mov_b32_e32 v213, v212
	s_waitcnt lgkmcnt(3)
	v_mfma_f32_32x32x16_bf16 v[80:95], v[242:245], v[96:99], v[80:95]
	ds_read_b128 v[242:245], v206
	s_mov_b32 m0, s49
	v_mad_i64_i32 v[254:255], s[0:1], s0, v180, v[168:169]
	global_load_lds_dwordx4 v[254:255], off
	s_add_u32 s100, s16, 0x100
	s_addc_u32 s101, s17, 0
	v_cvt_pk_bf16_f32 v152, v64, v65
	v_cvt_pk_bf16_f32 v153, v66, v67
	v_cvt_pk_bf16_f32 v154, v68, v69
	s_waitcnt lgkmcnt(3)
	s_nop 0
	v_mfma_f32_32x32x16_bf16 v[80:95], v[230:233], v[128:131], v[80:95]
	ds_read_b128 v[230:233], v193 offset:8192
	v_cvt_pk_bf16_f32 v155, v70, v71
	v_cvt_pk_bf16_f32 v156, v72, v73
	v_cvt_pk_bf16_f32 v157, v74, v75
	s_waitcnt lgkmcnt(3)
	s_nop 0
	v_mfma_f32_32x32x16_bf16 v[80:95], v[234:237], v[132:135], v[80:95]
	ds_read_b128 v[234:237], v186 offset:8192
	v_cvt_pk_bf16_f32 v158, v76, v77
	v_cvt_pk_bf16_f32 v159, v78, v79
	v_permlane32_swap_b32_e32 v212, v213
	s_waitcnt lgkmcnt(3)
	v_mfma_f32_32x32x16_bf16 v[80:95], v[238:241], v[136:139], v[80:95]
	ds_read_b128 v[238:241], v187 offset:8192
	v_add_f32_e32 v252, v212, v213
	v_fma_f32 v183, v207, v183, v252
	v_permlane32_swap_b32_e32 v152, v154
	s_waitcnt lgkmcnt(3)
	s_nop 0
	v_mfma_f32_32x32x16_bf16 v[80:95], v[242:245], v[140:143], v[80:95]
	ds_read_b128 v[242:245], v188 offset:8192
	v_permlane32_swap_b32_e32 v153, v155
	v_permlane32_swap_b32_e32 v156, v158
	v_permlane32_swap_b32_e32 v157, v159
	s_waitcnt lgkmcnt(3)
	v_mfma_f32_32x32x16_bf16 v[64:79], v[230:233], v[124:127], 0
	ds_read_b128 v[230:233], v189 offset:8192
	s_waitcnt lgkmcnt(3)
	s_nop 0
	v_mfma_f32_32x32x16_bf16 v[64:79], v[234:237], v[120:123], v[64:79]
	ds_read_b128 v[234:237], v190 offset:8192
	s_waitcnt lgkmcnt(3)
	s_nop 0
	v_mfma_f32_32x32x16_bf16 v[64:79], v[238:241], v[116:119], v[64:79]
	ds_read_b128 v[238:241], v191 offset:8192
	s_waitcnt lgkmcnt(3)
	s_nop 0
	v_mfma_f32_32x32x16_bf16 v[64:79], v[242:245], v[112:115], v[64:79]
	ds_read_b128 v[242:245], v192 offset:8192
	s_waitcnt lgkmcnt(3)
	s_nop 0
	v_mfma_f32_32x32x16_bf16 v[64:79], v[230:233], v[108:111], v[64:79]
	ds_read_b128 v[230:233], v203 offset:4096
	s_waitcnt lgkmcnt(3)
	s_nop 0
	v_mfma_f32_32x32x16_bf16 v[64:79], v[234:237], v[104:107], v[64:79]
	ds_read_b128 v[234:237], v204 offset:4096
	s_waitcnt lgkmcnt(3)
	s_nop 0
	v_mfma_f32_32x32x16_bf16 v[64:79], v[238:241], v[100:103], v[64:79]
	ds_read_b128 v[238:241], v205 offset:4096
	v_max_f32_e32 v249, v80, v81
	v_max3_f32 v249, v249, v82, v83
	s_waitcnt lgkmcnt(3)
	v_mfma_f32_32x32x16_bf16 v[64:79], v[242:245], v[96:99], v[64:79]
	ds_read_b128 v[242:245], v206 offset:4096
	v_max3_f32 v249, v249, v84, v85
	v_max3_f32 v249, v249, v86, v87
	s_waitcnt lgkmcnt(3)
	s_nop 0
	v_mfma_f32_32x32x16_bf16 v[64:79], v[230:233], v[128:131], v[64:79]
	ds_read_b64_tr_b16 v[214:215], v184
	ds_read_b64_tr_b16 v[216:217], v184 offset:2048
	v_max3_f32 v249, v249, v88, v89
	v_max3_f32 v249, v249, v90, v91
	s_waitcnt lgkmcnt(4)
	s_nop 0
	v_mfma_f32_32x32x16_bf16 v[64:79], v[234:237], v[132:135], v[64:79]
	ds_read_b64_tr_b16 v[218:219], v184 offset:4096
	ds_read_b64_tr_b16 v[220:221], v184 offset:6144
	v_max3_f32 v249, v249, v92, v93
	v_max3_f32 v249, v249, v94, v95
	s_waitcnt lgkmcnt(5)
	s_nop 0
	v_mfma_f32_32x32x16_bf16 v[64:79], v[238:241], v[136:139], v[64:79]
	ds_read_b64_tr_b16 v[222:223], v184 offset:8192
	ds_read_b64_tr_b16 v[224:225], v184 offset:10240
	s_waitcnt lgkmcnt(6)
	s_nop 0
	v_mfma_f32_32x32x16_bf16 v[64:79], v[242:245], v[140:143], v[64:79]
	ds_read_b64_tr_b16 v[226:227], v184 offset:12288
	ds_read_b64_tr_b16 v[228:229], v184 offset:14336
	s_waitcnt lgkmcnt(6)
	s_nop 0
	v_mfma_f32_32x32x16_bf16 v[0:15], v[214:217], v[144:147], v[0:15]
	ds_read_b64_tr_b16 v[214:215], v184 offset:512
	ds_read_b64_tr_b16 v[216:217], v184 offset:2560
	s_waitcnt lgkmcnt(6)
	s_nop 0
	v_mfma_f32_32x32x16_bf16 v[0:15], v[218:221], v[148:151], v[0:15]
	ds_read_b64_tr_b16 v[218:219], v184 offset:4608
	ds_read_b64_tr_b16 v[220:221], v184 offset:6656
	s_waitcnt lgkmcnt(6)
	s_nop 0
	v_mfma_f32_32x32x16_bf16 v[0:15], v[222:225], v[152:155], v[0:15]
	ds_read_b64_tr_b16 v[222:223], v184 offset:8704
	ds_read_b64_tr_b16 v[224:225], v184 offset:10752
	s_waitcnt lgkmcnt(6)
	s_nop 0
	v_mfma_f32_32x32x16_bf16 v[0:15], v[226:229], v[156:159], v[0:15]
	ds_read_b64_tr_b16 v[226:227], v184 offset:12800
	ds_read_b64_tr_b16 v[228:229], v184 offset:14848
	s_waitcnt lgkmcnt(6)
	s_nop 0
	v_mfma_f32_32x32x16_bf16 v[48:63], v[214:217], v[144:147], v[48:63]
	ds_read_b64_tr_b16 v[214:215], v184 offset:1024
	ds_read_b64_tr_b16 v[216:217], v184 offset:3072
	v_max3_f32 v249, v249, v64, v65
	v_max3_f32 v249, v249, v66, v67
	v_max3_f32 v249, v249, v68, v69
	v_max3_f32 v249, v249, v70, v71
	v_max3_f32 v249, v249, v72, v73
	v_max3_f32 v249, v249, v74, v75
	v_max3_f32 v249, v249, v76, v77
	v_max3_f32 v249, v249, v78, v79
	s_waitcnt lgkmcnt(6)
	s_nop 0
	v_mfma_f32_32x32x16_bf16 v[48:63], v[218:221], v[148:151], v[48:63]
	ds_read_b64_tr_b16 v[218:219], v184 offset:5120
	ds_read_b64_tr_b16 v[220:221], v184 offset:7168
	v_mov_b32_e32 v250, v249
	s_nop 1
	v_permlane32_swap_b32_e32 v249, v250
	v_max_f32_e32 v249, v249, v250
	v_sub_f32_e32 v250, v249, v208
	v_cmp_ge_f32_e32 vcc, s40, v250
	v_max_f32_e32 v249, v208, v249
	v_sub_f32_e32 v250, v208, v249
	s_waitcnt lgkmcnt(6)
	s_nop 0
	v_mfma_f32_32x32x16_bf16 v[48:63], v[222:225], v[152:155], v[48:63]
	ds_read_b64_tr_b16 v[222:223], v184 offset:9216
	ds_read_b64_tr_b16 v[224:225], v184 offset:11264
	v_mul_f32_e32 v250, 0x3dd53b94, v250
	v_exp_f32_e32 v250, v250
	s_cmp_eq_u64 vcc, exec
	s_cselect_b64 s[10:11], -1, 0
	v_cndmask_b32_e64 v207, v250, 1.0, s[10:11]
	v_cndmask_b32_e64 v208, v249, v208, s[10:11]
	v_mul_f32_e32 v251, 0xbdd53b94, v208
	v_fmamk_f32 v80, v80, 0x3dd53b94, v251
	s_waitcnt lgkmcnt(6)
	v_mfma_f32_32x32x16_bf16 v[48:63], v[226:229], v[156:159], v[48:63]
	ds_read_b64_tr_b16 v[226:227], v184 offset:13312
	ds_read_b64_tr_b16 v[228:229], v184 offset:15360
	v_fmamk_f32 v81, v81, 0x3dd53b94, v251
	v_fmamk_f32 v82, v82, 0x3dd53b94, v251
	v_fmamk_f32 v83, v83, 0x3dd53b94, v251
	v_fmamk_f32 v84, v84, 0x3dd53b94, v251
	v_fmamk_f32 v85, v85, 0x3dd53b94, v251
	v_fmamk_f32 v86, v86, 0x3dd53b94, v251
	v_fmamk_f32 v87, v87, 0x3dd53b94, v251
	s_waitcnt lgkmcnt(6)
	s_nop 0
	v_mfma_f32_32x32x16_bf16 v[32:47], v[214:217], v[144:147], v[32:47]
	ds_read_b64_tr_b16 v[214:215], v184 offset:1536
	ds_read_b64_tr_b16 v[216:217], v184 offset:3584
	v_fmamk_f32 v88, v88, 0x3dd53b94, v251
	v_fmamk_f32 v89, v89, 0x3dd53b94, v251
	v_fmamk_f32 v90, v90, 0x3dd53b94, v251
	v_fmamk_f32 v91, v91, 0x3dd53b94, v251
	v_fmamk_f32 v92, v92, 0x3dd53b94, v251
	v_fmamk_f32 v93, v93, 0x3dd53b94, v251
	v_fmamk_f32 v94, v94, 0x3dd53b94, v251
	s_waitcnt lgkmcnt(6)
	s_nop 0
	v_mfma_f32_32x32x16_bf16 v[32:47], v[218:221], v[148:151], v[32:47]
	ds_read_b64_tr_b16 v[218:219], v184 offset:5632
	ds_read_b64_tr_b16 v[220:221], v184 offset:7680
	v_fmamk_f32 v95, v95, 0x3dd53b94, v251
	v_exp_f32_e32 v80, v80
	v_fmamk_f32 v64, v64, 0x3dd53b94, v251
	v_exp_f32_e32 v81, v81
	v_fmamk_f32 v65, v65, 0x3dd53b94, v251
	v_add_f32_e32 v212, 0, v80
	v_exp_f32_e32 v82, v82
	s_waitcnt lgkmcnt(6)
	s_nop 0
	v_mfma_f32_32x32x16_bf16 v[32:47], v[222:225], v[152:155], v[32:47]
	ds_read_b64_tr_b16 v[222:223], v184 offset:9728
	ds_read_b64_tr_b16 v[224:225], v184 offset:11776
	v_fmamk_f32 v66, v66, 0x3dd53b94, v251
	v_add_f32_e32 v212, v81, v212
	v_exp_f32_e32 v83, v83
	v_fmamk_f32 v67, v67, 0x3dd53b94, v251
	v_add_f32_e32 v212, v82, v212
	v_exp_f32_e32 v84, v84
	v_fmamk_f32 v68, v68, 0x3dd53b94, v251
	s_waitcnt lgkmcnt(6)
	s_nop 0
	v_mfma_f32_32x32x16_bf16 v[32:47], v[226:229], v[156:159], v[32:47]
	ds_read_b64_tr_b16 v[226:227], v184 offset:13824
	ds_read_b64_tr_b16 v[228:229], v184 offset:15872
	v_add_f32_e32 v212, v83, v212
	v_exp_f32_e32 v85, v85
	v_fmamk_f32 v69, v69, 0x3dd53b94, v251
	v_add_f32_e32 v212, v84, v212
	v_exp_f32_e32 v86, v86
	v_fmamk_f32 v70, v70, 0x3dd53b94, v251
	v_add_f32_e32 v212, v85, v212
	s_waitcnt lgkmcnt(6)
	v_mfma_f32_32x32x16_bf16 v[16:31], v[214:217], v[144:147], v[16:31]
	v_exp_f32_e32 v87, v87
	v_fmamk_f32 v71, v71, 0x3dd53b94, v251
	v_add_f32_e32 v212, v86, v212
	v_exp_f32_e32 v88, v88
	v_fmamk_f32 v72, v72, 0x3dd53b94, v251
	v_add_f32_e32 v212, v87, v212
	v_exp_f32_e32 v89, v89
	s_waitcnt lgkmcnt(4)
	v_mfma_f32_32x32x16_bf16 v[16:31], v[218:221], v[148:151], v[16:31]
	v_fmamk_f32 v73, v73, 0x3dd53b94, v251
	v_add_f32_e32 v212, v88, v212
	v_exp_f32_e32 v90, v90
	v_fmamk_f32 v74, v74, 0x3dd53b94, v251
	v_add_f32_e32 v212, v89, v212
	v_exp_f32_e32 v91, v91
	v_fmamk_f32 v75, v75, 0x3dd53b94, v251
	s_waitcnt lgkmcnt(2)
	s_nop 0
	v_mfma_f32_32x32x16_bf16 v[16:31], v[222:225], v[152:155], v[16:31]
	v_add_f32_e32 v212, v90, v212
	v_exp_f32_e32 v92, v92
	v_fmamk_f32 v76, v76, 0x3dd53b94, v251
	v_add_f32_e32 v212, v91, v212
	v_exp_f32_e32 v93, v93
	v_fmamk_f32 v77, v77, 0x3dd53b94, v251
	v_add_f32_e32 v212, v92, v212
	s_waitcnt lgkmcnt(0)
	v_mfma_f32_32x32x16_bf16 v[16:31], v[226:229], v[156:159], v[16:31]
	v_exp_f32_e32 v94, v94
	v_fmamk_f32 v78, v78, 0x3dd53b94, v251
	v_add_f32_e32 v212, v93, v212
	v_exp_f32_e32 v95, v95
	v_fmamk_f32 v79, v79, 0x3dd53b94, v251
	v_add_f32_e32 v212, v94, v212
	v_add_f32_e32 v212, v95, v212
	v_cvt_pk_bf16_f32 v144, v80, v81
	v_cvt_pk_bf16_f32 v145, v82, v83
	v_cvt_pk_bf16_f32 v146, v84, v85
	v_cvt_pk_bf16_f32 v147, v86, v87
	v_cvt_pk_bf16_f32 v148, v88, v89
	v_cvt_pk_bf16_f32 v149, v90, v91
	v_cvt_pk_bf16_f32 v150, v92, v93
	v_cvt_pk_bf16_f32 v151, v94, v95
	v_permlane32_swap_b32_e32 v144, v146
	v_permlane32_swap_b32_e32 v145, v147
	v_permlane32_swap_b32_e32 v148, v150
	v_permlane32_swap_b32_e32 v149, v151
	v_cmp_gt_f32_e32 vcc, 1.0, v207
	s_cbranch_vccz .Lmla_noresc_e
	v_mul_f32_e32 v0, v207, v0
	v_mul_f32_e32 v1, v207, v1
	v_mul_f32_e32 v2, v207, v2
	v_mul_f32_e32 v3, v207, v3
	v_mul_f32_e32 v4, v207, v4
	v_mul_f32_e32 v5, v207, v5
	v_mul_f32_e32 v6, v207, v6
	v_mul_f32_e32 v7, v207, v7
	v_mul_f32_e32 v8, v207, v8
	v_mul_f32_e32 v9, v207, v9
	v_mul_f32_e32 v10, v207, v10
	v_mul_f32_e32 v11, v207, v11
	v_mul_f32_e32 v12, v207, v12
	v_mul_f32_e32 v13, v207, v13
	v_mul_f32_e32 v14, v207, v14
	v_mul_f32_e32 v15, v207, v15
	v_mul_f32_e32 v48, v207, v48
	v_mul_f32_e32 v49, v207, v49
	v_mul_f32_e32 v50, v207, v50
	v_mul_f32_e32 v51, v207, v51
	v_mul_f32_e32 v52, v207, v52
	v_mul_f32_e32 v53, v207, v53
	v_mul_f32_e32 v54, v207, v54
	v_mul_f32_e32 v55, v207, v55
	v_mul_f32_e32 v56, v207, v56
	v_mul_f32_e32 v57, v207, v57
	v_mul_f32_e32 v58, v207, v58
	v_mul_f32_e32 v59, v207, v59
	v_mul_f32_e32 v60, v207, v60
	v_mul_f32_e32 v61, v207, v61
	v_mul_f32_e32 v62, v207, v62
	v_mul_f32_e32 v63, v207, v63
	v_mul_f32_e32 v32, v207, v32
	v_mul_f32_e32 v33, v207, v33
	v_mul_f32_e32 v34, v207, v34
	v_mul_f32_e32 v35, v207, v35
	v_mul_f32_e32 v36, v207, v36
	v_mul_f32_e32 v37, v207, v37
	v_mul_f32_e32 v38, v207, v38
	v_mul_f32_e32 v39, v207, v39
	v_mul_f32_e32 v40, v207, v40
	v_mul_f32_e32 v41, v207, v41
	v_mul_f32_e32 v42, v207, v42
	v_mul_f32_e32 v43, v207, v43
	v_mul_f32_e32 v44, v207, v44
	v_mul_f32_e32 v45, v207, v45
	v_mul_f32_e32 v46, v207, v46
	v_mul_f32_e32 v47, v207, v47
	v_mul_f32_e32 v16, v207, v16
	v_mul_f32_e32 v17, v207, v17
	v_mul_f32_e32 v18, v207, v18
	v_mul_f32_e32 v19, v207, v19
	v_mul_f32_e32 v20, v207, v20
	v_mul_f32_e32 v21, v207, v21
	v_mul_f32_e32 v22, v207, v22
	v_mul_f32_e32 v23, v207, v23
	v_mul_f32_e32 v24, v207, v24
	v_mul_f32_e32 v25, v207, v25
	v_mul_f32_e32 v26, v207, v26
	v_mul_f32_e32 v27, v207, v27
	v_mul_f32_e32 v28, v207, v28
	v_mul_f32_e32 v29, v207, v29
	v_mul_f32_e32 v30, v207, v30
	v_mul_f32_e32 v31, v207, v31
.Lmla_noresc_e:
	s_add_i32 s58, s58, 1
	s_addk_i32 s51, 0x80
	s_waitcnt vmcnt(0) lgkmcnt(0)
	s_barrier
	s_cmp_ge_u32 s58, s19
	s_cbranch_scc0 .Lmla_loop
	ds_read_b128 v[230:233], v193 offset:24576
	ds_read_b128 v[234:237], v186 offset:24576
	ds_read_b128 v[238:241], v187 offset:24576
	ds_read_b128 v[242:245], v188 offset:24576
	v_exp_f32_e32 v64, v64
	v_exp_f32_e32 v65, v65
	v_add_f32_e32 v212, v64, v212
	v_exp_f32_e32 v66, v66
	v_add_f32_e32 v212, v65, v212
	v_exp_f32_e32 v67, v67
	s_waitcnt lgkmcnt(3)
	v_mfma_f32_32x32x16_bf16 v[80:95], v[230:233], v[124:127], 0
	ds_read_b128 v[230:233], v189 offset:24576
	s_mov_b32 m0, s54
	v_lshl_add_u64 v[254:255], v[164:165], 1, s[100:101]
	global_load_lds_dwordx4 v[254:255], off
	v_add_f32_e32 v212, v66, v212
	v_exp_f32_e32 v68, v68
	v_add_f32_e32 v212, v67, v212
	v_exp_f32_e32 v69, v69
	s_waitcnt lgkmcnt(3)
	v_mfma_f32_32x32x16_bf16 v[80:95], v[234:237], v[120:123], v[80:95]
	ds_read_b128 v[234:237], v190 offset:24576
	s_mov_b32 m0, s55
	v_lshl_add_u64 v[254:255], v[166:167], 1, s[100:101]
	global_load_lds_dwordx4 v[254:255], off
	v_add_f32_e32 v212, v68, v212
	v_exp_f32_e32 v70, v70
	v_add_f32_e32 v212, v69, v212
	v_exp_f32_e32 v71, v71
	s_waitcnt lgkmcnt(3)
	v_mfma_f32_32x32x16_bf16 v[80:95], v[238:241], v[116:119], v[80:95]
	ds_read_b128 v[238:241], v191 offset:24576
	v_add_f32_e32 v212, v70, v212
	v_exp_f32_e32 v72, v72
	v_add_f32_e32 v212, v71, v212
	v_exp_f32_e32 v73, v73
	s_waitcnt lgkmcnt(3)
	s_nop 0
	v_mfma_f32_32x32x16_bf16 v[80:95], v[242:245], v[112:115], v[80:95]
	ds_read_b128 v[242:245], v192 offset:24576
	v_add_f32_e32 v212, v72, v212
	v_exp_f32_e32 v74, v74
	v_add_f32_e32 v212, v73, v212
	v_exp_f32_e32 v75, v75
	s_waitcnt lgkmcnt(3)
	s_nop 0
	v_mfma_f32_32x32x16_bf16 v[80:95], v[230:233], v[108:111], v[80:95]
	ds_read_b128 v[230:233], v203 offset:24576
	v_add_f32_e32 v212, v74, v212
	v_exp_f32_e32 v76, v76
	v_add_f32_e32 v212, v75, v212
	v_exp_f32_e32 v77, v77
	s_waitcnt lgkmcnt(3)
	s_nop 0
	v_mfma_f32_32x32x16_bf16 v[80:95], v[234:237], v[104:107], v[80:95]
	ds_read_b128 v[234:237], v204 offset:24576
	v_add_f32_e32 v212, v76, v212
	v_exp_f32_e32 v78, v78
	v_add_f32_e32 v212, v77, v212
	v_exp_f32_e32 v79, v79
	s_waitcnt lgkmcnt(3)
	s_nop 0
	v_mfma_f32_32x32x16_bf16 v[80:95], v[238:241], v[100:103], v[80:95]
	ds_read_b128 v[238:241], v205 offset:24576
	v_add_f32_e32 v212, v78, v212
	v_add_f32_e32 v212, v79, v212
	v_mov_b32_e32 v213, v212
	s_waitcnt lgkmcnt(3)
	v_mfma_f32_32x32x16_bf16 v[80:95], v[242:245], v[96:99], v[80:95]
	ds_read_b128 v[242:245], v206 offset:24576
	v_cvt_pk_bf16_f32 v152, v64, v65
	v_cvt_pk_bf16_f32 v153, v66, v67
	v_cvt_pk_bf16_f32 v154, v68, v69
	s_waitcnt lgkmcnt(3)
	s_nop 0
	v_mfma_f32_32x32x16_bf16 v[80:95], v[230:233], v[128:131], v[80:95]
	ds_read_b128 v[230:233], v193 offset:32768
	v_cvt_pk_bf16_f32 v155, v70, v71
	v_cvt_pk_bf16_f32 v156, v72, v73
	v_cvt_pk_bf16_f32 v157, v74, v75
	s_waitcnt lgkmcnt(3)
	s_nop 0
	v_mfma_f32_32x32x16_bf16 v[80:95], v[234:237], v[132:135], v[80:95]
	ds_read_b128 v[234:237], v186 offset:32768
	v_cvt_pk_bf16_f32 v158, v76, v77
	v_cvt_pk_bf16_f32 v159, v78, v79
	v_permlane32_swap_b32_e32 v212, v213
	s_waitcnt lgkmcnt(3)
	v_mfma_f32_32x32x16_bf16 v[80:95], v[238:241], v[136:139], v[80:95]
	ds_read_b128 v[238:241], v187 offset:32768
	v_add_f32_e32 v252, v212, v213
	v_fma_f32 v183, v207, v183, v252
	v_permlane32_swap_b32_e32 v152, v154
	s_waitcnt lgkmcnt(3)
	s_nop 0
	v_mfma_f32_32x32x16_bf16 v[80:95], v[242:245], v[140:143], v[80:95]
	ds_read_b128 v[242:245], v188 offset:32768
	v_permlane32_swap_b32_e32 v153, v155
	v_permlane32_swap_b32_e32 v156, v158
	v_permlane32_swap_b32_e32 v157, v159
	s_waitcnt lgkmcnt(3)
	v_mfma_f32_32x32x16_bf16 v[64:79], v[230:233], v[124:127], 0
	ds_read_b128 v[230:233], v189 offset:32768
	s_waitcnt lgkmcnt(3)
	s_nop 0
	v_mfma_f32_32x32x16_bf16 v[64:79], v[234:237], v[120:123], v[64:79]
	ds_read_b128 v[234:237], v190 offset:32768
	s_waitcnt lgkmcnt(3)
	s_nop 0
	v_mfma_f32_32x32x16_bf16 v[64:79], v[238:241], v[116:119], v[64:79]
	ds_read_b128 v[238:241], v191 offset:32768
	s_waitcnt lgkmcnt(3)
	s_nop 0
	v_mfma_f32_32x32x16_bf16 v[64:79], v[242:245], v[112:115], v[64:79]
	ds_read_b128 v[242:245], v192 offset:32768
	s_waitcnt lgkmcnt(3)
	s_nop 0
	v_mfma_f32_32x32x16_bf16 v[64:79], v[230:233], v[108:111], v[64:79]
	ds_read_b128 v[230:233], v203 offset:28672
	s_waitcnt lgkmcnt(3)
	s_nop 0
	v_mfma_f32_32x32x16_bf16 v[64:79], v[234:237], v[104:107], v[64:79]
	ds_read_b128 v[234:237], v204 offset:28672
	s_waitcnt lgkmcnt(3)
	s_nop 0
	v_mfma_f32_32x32x16_bf16 v[64:79], v[238:241], v[100:103], v[64:79]
	ds_read_b128 v[238:241], v205 offset:28672
	v_max_f32_e32 v249, v80, v81
	v_max3_f32 v249, v249, v82, v83
	s_waitcnt lgkmcnt(3)
	v_mfma_f32_32x32x16_bf16 v[64:79], v[242:245], v[96:99], v[64:79]
	ds_read_b128 v[242:245], v206 offset:28672
	v_max3_f32 v249, v249, v84, v85
	v_max3_f32 v249, v249, v86, v87
	s_waitcnt lgkmcnt(3)
	s_nop 0
	v_mfma_f32_32x32x16_bf16 v[64:79], v[230:233], v[128:131], v[64:79]
	ds_read_b64_tr_b16 v[214:215], v185
	ds_read_b64_tr_b16 v[216:217], v185 offset:2048
	v_max3_f32 v249, v249, v88, v89
	v_max3_f32 v249, v249, v90, v91
	s_waitcnt lgkmcnt(4)
	s_nop 0
	v_mfma_f32_32x32x16_bf16 v[64:79], v[234:237], v[132:135], v[64:79]
	ds_read_b64_tr_b16 v[218:219], v185 offset:4096
	ds_read_b64_tr_b16 v[220:221], v185 offset:6144
	v_max3_f32 v249, v249, v92, v93
	v_max3_f32 v249, v249, v94, v95
	s_waitcnt lgkmcnt(5)
	s_nop 0
	v_mfma_f32_32x32x16_bf16 v[64:79], v[238:241], v[136:139], v[64:79]
	ds_read_b64_tr_b16 v[222:223], v185 offset:8192
	ds_read_b64_tr_b16 v[224:225], v185 offset:10240
	s_waitcnt lgkmcnt(6)
	s_nop 0
	v_mfma_f32_32x32x16_bf16 v[64:79], v[242:245], v[140:143], v[64:79]
	ds_read_b64_tr_b16 v[226:227], v185 offset:12288
	ds_read_b64_tr_b16 v[228:229], v185 offset:14336
	s_waitcnt lgkmcnt(6)
	s_nop 0
	v_mfma_f32_32x32x16_bf16 v[0:15], v[214:217], v[144:147], v[0:15]
	ds_read_b64_tr_b16 v[214:215], v185 offset:512
	ds_read_b64_tr_b16 v[216:217], v185 offset:2560
	s_waitcnt lgkmcnt(6)
	s_nop 0
	v_mfma_f32_32x32x16_bf16 v[0:15], v[218:221], v[148:151], v[0:15]
	ds_read_b64_tr_b16 v[218:219], v185 offset:4608
	ds_read_b64_tr_b16 v[220:221], v185 offset:6656
	s_waitcnt lgkmcnt(6)
	s_nop 0
	v_mfma_f32_32x32x16_bf16 v[0:15], v[222:225], v[152:155], v[0:15]
	ds_read_b64_tr_b16 v[222:223], v185 offset:8704
	ds_read_b64_tr_b16 v[224:225], v185 offset:10752
	s_waitcnt lgkmcnt(6)
	s_nop 0
	v_mfma_f32_32x32x16_bf16 v[0:15], v[226:229], v[156:159], v[0:15]
	ds_read_b64_tr_b16 v[226:227], v185 offset:12800
	ds_read_b64_tr_b16 v[228:229], v185 offset:14848
	s_waitcnt lgkmcnt(6)
	s_nop 0
	v_mfma_f32_32x32x16_bf16 v[48:63], v[214:217], v[144:147], v[48:63]
	ds_read_b64_tr_b16 v[214:215], v185 offset:1024
	ds_read_b64_tr_b16 v[216:217], v185 offset:3072
	v_max3_f32 v249, v249, v64, v65
	v_max3_f32 v249, v249, v66, v67
	v_max3_f32 v249, v249, v68, v69
	v_max3_f32 v249, v249, v70, v71
	v_max3_f32 v249, v249, v72, v73
	v_max3_f32 v249, v249, v74, v75
	v_max3_f32 v249, v249, v76, v77
	v_max3_f32 v249, v249, v78, v79
	s_waitcnt lgkmcnt(6)
	s_nop 0
	v_mfma_f32_32x32x16_bf16 v[48:63], v[218:221], v[148:151], v[48:63]
	ds_read_b64_tr_b16 v[218:219], v185 offset:5120
	ds_read_b64_tr_b16 v[220:221], v185 offset:7168
	v_mov_b32_e32 v250, v249
	s_nop 1
	v_permlane32_swap_b32_e32 v249, v250
	v_max_f32_e32 v249, v249, v250
	v_sub_f32_e32 v250, v249, v208
	v_cmp_ge_f32_e32 vcc, s40, v250
	v_max_f32_e32 v249, v208, v249
	v_sub_f32_e32 v250, v208, v249
	s_waitcnt lgkmcnt(6)
	s_nop 0
	v_mfma_f32_32x32x16_bf16 v[48:63], v[222:225], v[152:155], v[48:63]
	ds_read_b64_tr_b16 v[222:223], v185 offset:9216
	ds_read_b64_tr_b16 v[224:225], v185 offset:11264
	v_mul_f32_e32 v250, 0x3dd53b94, v250
	v_exp_f32_e32 v250, v250
	s_cmp_eq_u64 vcc, exec
	s_cselect_b64 s[10:11], -1, 0
	v_cndmask_b32_e64 v207, v250, 1.0, s[10:11]
	v_cndmask_b32_e64 v208, v249, v208, s[10:11]
	v_mul_f32_e32 v251, 0xbdd53b94, v208
	v_fmamk_f32 v80, v80, 0x3dd53b94, v251
	s_waitcnt lgkmcnt(6)
	v_mfma_f32_32x32x16_bf16 v[48:63], v[226:229], v[156:159], v[48:63]
	ds_read_b64_tr_b16 v[226:227], v185 offset:13312
	ds_read_b64_tr_b16 v[228:229], v185 offset:15360
	v_fmamk_f32 v81, v81, 0x3dd53b94, v251
	v_fmamk_f32 v82, v82, 0x3dd53b94, v251
	v_fmamk_f32 v83, v83, 0x3dd53b94, v251
	v_fmamk_f32 v84, v84, 0x3dd53b94, v251
	v_fmamk_f32 v85, v85, 0x3dd53b94, v251
	v_fmamk_f32 v86, v86, 0x3dd53b94, v251
	v_fmamk_f32 v87, v87, 0x3dd53b94, v251
	s_waitcnt lgkmcnt(6)
	s_nop 0
	v_mfma_f32_32x32x16_bf16 v[32:47], v[214:217], v[144:147], v[32:47]
	ds_read_b64_tr_b16 v[214:215], v185 offset:1536
	ds_read_b64_tr_b16 v[216:217], v185 offset:3584
	v_fmamk_f32 v88, v88, 0x3dd53b94, v251
	v_fmamk_f32 v89, v89, 0x3dd53b94, v251
	v_fmamk_f32 v90, v90, 0x3dd53b94, v251
	v_fmamk_f32 v91, v91, 0x3dd53b94, v251
	v_fmamk_f32 v92, v92, 0x3dd53b94, v251
	v_fmamk_f32 v93, v93, 0x3dd53b94, v251
	v_fmamk_f32 v94, v94, 0x3dd53b94, v251
	s_waitcnt lgkmcnt(6)
	s_nop 0
	v_mfma_f32_32x32x16_bf16 v[32:47], v[218:221], v[148:151], v[32:47]
	ds_read_b64_tr_b16 v[218:219], v185 offset:5632
	ds_read_b64_tr_b16 v[220:221], v185 offset:7680
	v_fmamk_f32 v95, v95, 0x3dd53b94, v251
	v_exp_f32_e32 v80, v80
	v_fmamk_f32 v64, v64, 0x3dd53b94, v251
	v_exp_f32_e32 v81, v81
	v_fmamk_f32 v65, v65, 0x3dd53b94, v251
	v_add_f32_e32 v212, 0, v80
	v_exp_f32_e32 v82, v82
	s_waitcnt lgkmcnt(6)
	s_nop 0
	v_mfma_f32_32x32x16_bf16 v[32:47], v[222:225], v[152:155], v[32:47]
	ds_read_b64_tr_b16 v[222:223], v185 offset:9728
	ds_read_b64_tr_b16 v[224:225], v185 offset:11776
	v_fmamk_f32 v66, v66, 0x3dd53b94, v251
	v_add_f32_e32 v212, v81, v212
	v_exp_f32_e32 v83, v83
	v_fmamk_f32 v67, v67, 0x3dd53b94, v251
	v_add_f32_e32 v212, v82, v212
	v_exp_f32_e32 v84, v84
	v_fmamk_f32 v68, v68, 0x3dd53b94, v251
	s_waitcnt lgkmcnt(6)
	s_nop 0
	v_mfma_f32_32x32x16_bf16 v[32:47], v[226:229], v[156:159], v[32:47]
	ds_read_b64_tr_b16 v[226:227], v185 offset:13824
	ds_read_b64_tr_b16 v[228:229], v185 offset:15872
	v_add_f32_e32 v212, v83, v212
	v_exp_f32_e32 v85, v85
	v_fmamk_f32 v69, v69, 0x3dd53b94, v251
	v_add_f32_e32 v212, v84, v212
	v_exp_f32_e32 v86, v86
	v_fmamk_f32 v70, v70, 0x3dd53b94, v251
	v_add_f32_e32 v212, v85, v212
	s_waitcnt lgkmcnt(6)
	v_mfma_f32_32x32x16_bf16 v[16:31], v[214:217], v[144:147], v[16:31]
	v_exp_f32_e32 v87, v87
	v_fmamk_f32 v71, v71, 0x3dd53b94, v251
	v_add_f32_e32 v212, v86, v212
	v_exp_f32_e32 v88, v88
	v_fmamk_f32 v72, v72, 0x3dd53b94, v251
	v_add_f32_e32 v212, v87, v212
	v_exp_f32_e32 v89, v89
	s_waitcnt lgkmcnt(4)
	v_mfma_f32_32x32x16_bf16 v[16:31], v[218:221], v[148:151], v[16:31]
	v_fmamk_f32 v73, v73, 0x3dd53b94, v251
	v_add_f32_e32 v212, v88, v212
	v_exp_f32_e32 v90, v90
	v_fmamk_f32 v74, v74, 0x3dd53b94, v251
	v_add_f32_e32 v212, v89, v212
	v_exp_f32_e32 v91, v91
	v_fmamk_f32 v75, v75, 0x3dd53b94, v251
	s_waitcnt lgkmcnt(2)
	s_nop 0
	v_mfma_f32_32x32x16_bf16 v[16:31], v[222:225], v[152:155], v[16:31]
	v_add_f32_e32 v212, v90, v212
	v_exp_f32_e32 v92, v92
	v_fmamk_f32 v76, v76, 0x3dd53b94, v251
	v_add_f32_e32 v212, v91, v212
	v_exp_f32_e32 v93, v93
	v_fmamk_f32 v77, v77, 0x3dd53b94, v251
	v_add_f32_e32 v212, v92, v212
	s_waitcnt lgkmcnt(0)
	v_mfma_f32_32x32x16_bf16 v[16:31], v[226:229], v[156:159], v[16:31]
	v_exp_f32_e32 v94, v94
	v_fmamk_f32 v78, v78, 0x3dd53b94, v251
	v_add_f32_e32 v212, v93, v212
	v_exp_f32_e32 v95, v95
	v_fmamk_f32 v79, v79, 0x3dd53b94, v251
	v_add_f32_e32 v212, v94, v212
	v_add_f32_e32 v212, v95, v212
	v_cvt_pk_bf16_f32 v144, v80, v81
	v_cvt_pk_bf16_f32 v145, v82, v83
	v_cvt_pk_bf16_f32 v146, v84, v85
	v_cvt_pk_bf16_f32 v147, v86, v87
	v_cvt_pk_bf16_f32 v148, v88, v89
	v_cvt_pk_bf16_f32 v149, v90, v91
	v_cvt_pk_bf16_f32 v150, v92, v93
	v_cvt_pk_bf16_f32 v151, v94, v95
	v_permlane32_swap_b32_e32 v144, v146
	v_permlane32_swap_b32_e32 v145, v147
	v_permlane32_swap_b32_e32 v148, v150
	v_permlane32_swap_b32_e32 v149, v151
	v_cmp_gt_f32_e32 vcc, 1.0, v207
	s_cbranch_vccz .Lmla_noresc_t
	v_mul_f32_e32 v0, v207, v0
	v_mul_f32_e32 v1, v207, v1
	v_mul_f32_e32 v2, v207, v2
	v_mul_f32_e32 v3, v207, v3
	v_mul_f32_e32 v4, v207, v4
	v_mul_f32_e32 v5, v207, v5
	v_mul_f32_e32 v6, v207, v6
	v_mul_f32_e32 v7, v207, v7
	v_mul_f32_e32 v8, v207, v8
	v_mul_f32_e32 v9, v207, v9
	v_mul_f32_e32 v10, v207, v10
	v_mul_f32_e32 v11, v207, v11
	v_mul_f32_e32 v12, v207, v12
	v_mul_f32_e32 v13, v207, v13
	v_mul_f32_e32 v14, v207, v14
	v_mul_f32_e32 v15, v207, v15
	v_mul_f32_e32 v48, v207, v48
	v_mul_f32_e32 v49, v207, v49
	v_mul_f32_e32 v50, v207, v50
	v_mul_f32_e32 v51, v207, v51
	v_mul_f32_e32 v52, v207, v52
	v_mul_f32_e32 v53, v207, v53
	v_mul_f32_e32 v54, v207, v54
	v_mul_f32_e32 v55, v207, v55
	v_mul_f32_e32 v56, v207, v56
	v_mul_f32_e32 v57, v207, v57
	v_mul_f32_e32 v58, v207, v58
	v_mul_f32_e32 v59, v207, v59
	v_mul_f32_e32 v60, v207, v60
	v_mul_f32_e32 v61, v207, v61
	v_mul_f32_e32 v62, v207, v62
	v_mul_f32_e32 v63, v207, v63
	v_mul_f32_e32 v32, v207, v32
	v_mul_f32_e32 v33, v207, v33
	v_mul_f32_e32 v34, v207, v34
	v_mul_f32_e32 v35, v207, v35
	v_mul_f32_e32 v36, v207, v36
	v_mul_f32_e32 v37, v207, v37
	v_mul_f32_e32 v38, v207, v38
	v_mul_f32_e32 v39, v207, v39
	v_mul_f32_e32 v40, v207, v40
	v_mul_f32_e32 v41, v207, v41
	v_mul_f32_e32 v42, v207, v42
	v_mul_f32_e32 v43, v207, v43
	v_mul_f32_e32 v44, v207, v44
	v_mul_f32_e32 v45, v207, v45
	v_mul_f32_e32 v46, v207, v46
	v_mul_f32_e32 v47, v207, v47
	v_mul_f32_e32 v16, v207, v16
	v_mul_f32_e32 v17, v207, v17
	v_mul_f32_e32 v18, v207, v18
	v_mul_f32_e32 v19, v207, v19
	v_mul_f32_e32 v20, v207, v20
	v_mul_f32_e32 v21, v207, v21
	v_mul_f32_e32 v22, v207, v22
	v_mul_f32_e32 v23, v207, v23
	v_mul_f32_e32 v24, v207, v24
	v_mul_f32_e32 v25, v207, v25
	v_mul_f32_e32 v26, v207, v26
	v_mul_f32_e32 v27, v207, v27
	v_mul_f32_e32 v28, v207, v28
	v_mul_f32_e32 v29, v207, v29
	v_mul_f32_e32 v30, v207, v30
	v_mul_f32_e32 v31, v207, v31
.Lmla_noresc_t:
	s_waitcnt vmcnt(0) lgkmcnt(0)
	s_barrier
	ds_read_b64_tr_b16 v[214:215], v184
	ds_read_b64_tr_b16 v[216:217], v184 offset:2048
	ds_read_b64_tr_b16 v[218:219], v184 offset:4096
	ds_read_b64_tr_b16 v[220:221], v184 offset:6144
	ds_read_b64_tr_b16 v[222:223], v184 offset:8192
	ds_read_b64_tr_b16 v[224:225], v184 offset:10240
	ds_read_b64_tr_b16 v[226:227], v184 offset:12288
	ds_read_b64_tr_b16 v[228:229], v184 offset:14336
	v_exp_f32_e32 v64, v64
	v_exp_f32_e32 v65, v65
	v_add_f32_e32 v212, v64, v212
	v_exp_f32_e32 v66, v66
	v_add_f32_e32 v212, v65, v212
	v_exp_f32_e32 v67, v67
	v_add_f32_e32 v212, v66, v212
	v_exp_f32_e32 v68, v68
	v_add_f32_e32 v212, v67, v212
	v_exp_f32_e32 v69, v69
	v_add_f32_e32 v212, v68, v212
	v_exp_f32_e32 v70, v70
	v_add_f32_e32 v212, v69, v212
	v_exp_f32_e32 v71, v71
	v_add_f32_e32 v212, v70, v212
	v_exp_f32_e32 v72, v72
	v_add_f32_e32 v212, v71, v212
	v_exp_f32_e32 v73, v73
	v_add_f32_e32 v212, v72, v212
	v_exp_f32_e32 v74, v74
	v_add_f32_e32 v212, v73, v212
	v_exp_f32_e32 v75, v75
	v_add_f32_e32 v212, v74, v212
	v_exp_f32_e32 v76, v76
	v_add_f32_e32 v212, v75, v212
	v_exp_f32_e32 v77, v77
	v_add_f32_e32 v212, v76, v212
	v_exp_f32_e32 v78, v78
	v_add_f32_e32 v212, v77, v212
	v_exp_f32_e32 v79, v79
	v_add_f32_e32 v212, v78, v212
	v_add_f32_e32 v212, v79, v212
	v_mov_b32_e32 v213, v212
	v_cvt_pk_bf16_f32 v152, v64, v65
	v_cvt_pk_bf16_f32 v153, v66, v67
	v_cvt_pk_bf16_f32 v154, v68, v69
	v_cvt_pk_bf16_f32 v155, v70, v71
	v_cvt_pk_bf16_f32 v156, v72, v73
	v_cvt_pk_bf16_f32 v157, v74, v75
	v_cvt_pk_bf16_f32 v158, v76, v77
	v_cvt_pk_bf16_f32 v159, v78, v79
	v_permlane32_swap_b32_e32 v212, v213
	v_add_f32_e32 v252, v212, v213
	v_fma_f32 v183, v207, v183, v252
	v_permlane32_swap_b32_e32 v152, v154
	v_permlane32_swap_b32_e32 v153, v155
	v_permlane32_swap_b32_e32 v156, v158
	v_permlane32_swap_b32_e32 v157, v159
	s_waitcnt lgkmcnt(6)
	s_nop 0
	v_mfma_f32_32x32x16_bf16 v[0:15], v[214:217], v[144:147], v[0:15]
	ds_read_b64_tr_b16 v[214:215], v184 offset:512
	ds_read_b64_tr_b16 v[216:217], v184 offset:2560
	s_waitcnt lgkmcnt(6)
	s_nop 0
	v_mfma_f32_32x32x16_bf16 v[0:15], v[218:221], v[148:151], v[0:15]
	ds_read_b64_tr_b16 v[218:219], v184 offset:4608
	ds_read_b64_tr_b16 v[220:221], v184 offset:6656
	s_waitcnt lgkmcnt(6)
	s_nop 0
	v_mfma_f32_32x32x16_bf16 v[0:15], v[222:225], v[152:155], v[0:15]
	ds_read_b64_tr_b16 v[222:223], v184 offset:8704
	ds_read_b64_tr_b16 v[224:225], v184 offset:10752
	s_waitcnt lgkmcnt(6)
	s_nop 0
	v_mfma_f32_32x32x16_bf16 v[0:15], v[226:229], v[156:159], v[0:15]
	ds_read_b64_tr_b16 v[226:227], v184 offset:12800
	ds_read_b64_tr_b16 v[228:229], v184 offset:14848
	s_waitcnt lgkmcnt(6)
	s_nop 0
	v_mfma_f32_32x32x16_bf16 v[48:63], v[214:217], v[144:147], v[48:63]
	ds_read_b64_tr_b16 v[214:215], v184 offset:1024
	ds_read_b64_tr_b16 v[216:217], v184 offset:3072
	s_waitcnt lgkmcnt(6)
	s_nop 0
	v_mfma_f32_32x32x16_bf16 v[48:63], v[218:221], v[148:151], v[48:63]
	ds_read_b64_tr_b16 v[218:219], v184 offset:5120
	ds_read_b64_tr_b16 v[220:221], v184 offset:7168
	s_waitcnt lgkmcnt(6)
	s_nop 0
	v_mfma_f32_32x32x16_bf16 v[48:63], v[222:225], v[152:155], v[48:63]
	ds_read_b64_tr_b16 v[222:223], v184 offset:9216
	ds_read_b64_tr_b16 v[224:225], v184 offset:11264
	s_waitcnt lgkmcnt(6)
	s_nop 0
	v_mfma_f32_32x32x16_bf16 v[48:63], v[226:229], v[156:159], v[48:63]
	ds_read_b64_tr_b16 v[226:227], v184 offset:13312
	ds_read_b64_tr_b16 v[228:229], v184 offset:15360
	s_waitcnt lgkmcnt(6)
	s_nop 0
	v_mfma_f32_32x32x16_bf16 v[32:47], v[214:217], v[144:147], v[32:47]
	ds_read_b64_tr_b16 v[214:215], v184 offset:1536
	ds_read_b64_tr_b16 v[216:217], v184 offset:3584
	s_waitcnt lgkmcnt(6)
	s_nop 0
	v_mfma_f32_32x32x16_bf16 v[32:47], v[218:221], v[148:151], v[32:47]
	ds_read_b64_tr_b16 v[218:219], v184 offset:5632
	ds_read_b64_tr_b16 v[220:221], v184 offset:7680
	s_waitcnt lgkmcnt(6)
	s_nop 0
	v_mfma_f32_32x32x16_bf16 v[32:47], v[222:225], v[152:155], v[32:47]
	ds_read_b64_tr_b16 v[222:223], v184 offset:9728
	ds_read_b64_tr_b16 v[224:225], v184 offset:11776
	s_waitcnt lgkmcnt(6)
	s_nop 0
	v_mfma_f32_32x32x16_bf16 v[32:47], v[226:229], v[156:159], v[32:47]
	ds_read_b64_tr_b16 v[226:227], v184 offset:13824
	ds_read_b64_tr_b16 v[228:229], v184 offset:15872
	s_waitcnt lgkmcnt(6)
	s_nop 0
	v_mfma_f32_32x32x16_bf16 v[16:31], v[214:217], v[144:147], v[16:31]
	s_waitcnt lgkmcnt(4)
	s_nop 0
	v_mfma_f32_32x32x16_bf16 v[16:31], v[218:221], v[148:151], v[16:31]
	s_waitcnt lgkmcnt(2)
	s_nop 0
	v_mfma_f32_32x32x16_bf16 v[16:31], v[222:225], v[152:155], v[16:31]
	s_waitcnt lgkmcnt(0)
	s_nop 0
	v_mfma_f32_32x32x16_bf16 v[16:31], v[226:229], v[156:159], v[16:31]
	s_setprio 0
	s_ashr_i32 s13, s12, 31
	s_lshl_b64 s[0:1], s[12:13], 12
	s_add_u32 s0, s4, s0
	s_addc_u32 s1, s5, s1
	v_rcp_f32_e32 v213, v183
	v_lshlrev_b32_e32 v160, 12, v170
	v_lshl_add_u32 v160, v171, 4, v160
	s_nop 1
	v_lshl_add_u64 v[254:255], s[0:1], 0, v[160:161]
	v_mul_f32_e32 v0, v213, v0
	v_mul_f32_e32 v1, v213, v1
	v_mul_f32_e32 v2, v213, v2
	v_mul_f32_e32 v3, v213, v3
	v_mul_f32_e32 v4, v213, v4
	v_mul_f32_e32 v5, v213, v5
	v_mul_f32_e32 v6, v213, v6
	v_mul_f32_e32 v7, v213, v7
	v_mul_f32_e32 v8, v213, v8
	v_mul_f32_e32 v9, v213, v9
	v_mul_f32_e32 v10, v213, v10
	v_mul_f32_e32 v11, v213, v11
	v_mul_f32_e32 v12, v213, v12
	v_mul_f32_e32 v13, v213, v13
	v_mul_f32_e32 v14, v213, v14
	v_mul_f32_e32 v15, v213, v15
	v_cvt_pk_bf16_f32 v0, v0, v1
	v_cvt_pk_bf16_f32 v1, v2, v3
	v_cvt_pk_bf16_f32 v2, v4, v5
	v_cvt_pk_bf16_f32 v3, v6, v7
	v_cvt_pk_bf16_f32 v4, v8, v9
	v_cvt_pk_bf16_f32 v5, v10, v11
	v_cvt_pk_bf16_f32 v6, v12, v13
	v_cvt_pk_bf16_f32 v7, v14, v15
	s_nop 1
	v_permlane32_swap_b32_e32 v0, v2
	v_permlane32_swap_b32_e32 v1, v3
	v_permlane32_swap_b32_e32 v4, v6
	v_permlane32_swap_b32_e32 v5, v7
	global_store_dwordx4 v[254:255], v[0:3], off
	global_store_dwordx4 v[254:255], v[4:7], off offset:32
	v_mul_f32_e32 v48, v213, v48
	v_mul_f32_e32 v49, v213, v49
	v_mul_f32_e32 v50, v213, v50
	v_mul_f32_e32 v51, v213, v51
	v_mul_f32_e32 v52, v213, v52
	v_mul_f32_e32 v53, v213, v53
	v_mul_f32_e32 v54, v213, v54
	v_mul_f32_e32 v55, v213, v55
	v_mul_f32_e32 v56, v213, v56
	v_mul_f32_e32 v57, v213, v57
	v_mul_f32_e32 v58, v213, v58
	v_mul_f32_e32 v59, v213, v59
	v_mul_f32_e32 v60, v213, v60
	v_mul_f32_e32 v61, v213, v61
	v_mul_f32_e32 v62, v213, v62
	v_mul_f32_e32 v63, v213, v63
	v_cvt_pk_bf16_f32 v48, v48, v49
	v_cvt_pk_bf16_f32 v49, v50, v51
	v_cvt_pk_bf16_f32 v50, v52, v53
	v_cvt_pk_bf16_f32 v51, v54, v55
	v_cvt_pk_bf16_f32 v52, v56, v57
	v_cvt_pk_bf16_f32 v53, v58, v59
	v_cvt_pk_bf16_f32 v54, v60, v61
	v_cvt_pk_bf16_f32 v55, v62, v63
	s_nop 1
	v_permlane32_swap_b32_e32 v48, v50
	v_permlane32_swap_b32_e32 v49, v51
	v_permlane32_swap_b32_e32 v52, v54
	v_permlane32_swap_b32_e32 v53, v55
	global_store_dwordx4 v[254:255], v[48:51], off offset:64
	global_store_dwordx4 v[254:255], v[52:55], off offset:96
	v_mul_f32_e32 v32, v213, v32
	v_mul_f32_e32 v33, v213, v33
	v_mul_f32_e32 v34, v213, v34
	v_mul_f32_e32 v35, v213, v35
	v_mul_f32_e32 v36, v213, v36
	v_mul_f32_e32 v37, v213, v37
	v_mul_f32_e32 v38, v213, v38
	v_mul_f32_e32 v39, v213, v39
	v_mul_f32_e32 v40, v213, v40
	v_mul_f32_e32 v41, v213, v41
	v_mul_f32_e32 v42, v213, v42
	v_mul_f32_e32 v43, v213, v43
	v_mul_f32_e32 v44, v213, v44
	v_mul_f32_e32 v45, v213, v45
	v_mul_f32_e32 v46, v213, v46
	v_mul_f32_e32 v47, v213, v47
	v_cvt_pk_bf16_f32 v32, v32, v33
	v_cvt_pk_bf16_f32 v33, v34, v35
	v_cvt_pk_bf16_f32 v34, v36, v37
	v_cvt_pk_bf16_f32 v35, v38, v39
	v_cvt_pk_bf16_f32 v36, v40, v41
	v_cvt_pk_bf16_f32 v37, v42, v43
	v_cvt_pk_bf16_f32 v38, v44, v45
	v_cvt_pk_bf16_f32 v39, v46, v47
	s_nop 1
	v_permlane32_swap_b32_e32 v32, v34
	v_permlane32_swap_b32_e32 v33, v35
	v_permlane32_swap_b32_e32 v36, v38
	v_permlane32_swap_b32_e32 v37, v39
	global_store_dwordx4 v[254:255], v[32:35], off offset:128
	global_store_dwordx4 v[254:255], v[36:39], off offset:160
	v_mul_f32_e32 v16, v213, v16
	v_mul_f32_e32 v17, v213, v17
	v_mul_f32_e32 v18, v213, v18
	v_mul_f32_e32 v19, v213, v19
	v_mul_f32_e32 v20, v213, v20
	v_mul_f32_e32 v21, v213, v21
	v_mul_f32_e32 v22, v213, v22
	v_mul_f32_e32 v23, v213, v23
	v_mul_f32_e32 v24, v213, v24
	v_mul_f32_e32 v25, v213, v25
	v_mul_f32_e32 v26, v213, v26
	v_mul_f32_e32 v27, v213, v27
	v_mul_f32_e32 v28, v213, v28
	v_mul_f32_e32 v29, v213, v29
	v_mul_f32_e32 v30, v213, v30
	v_mul_f32_e32 v31, v213, v31
	v_cvt_pk_bf16_f32 v16, v16, v17
	v_cvt_pk_bf16_f32 v17, v18, v19
	v_cvt_pk_bf16_f32 v18, v20, v21
	v_cvt_pk_bf16_f32 v19, v22, v23
	v_cvt_pk_bf16_f32 v20, v24, v25
	v_cvt_pk_bf16_f32 v21, v26, v27
	v_cvt_pk_bf16_f32 v22, v28, v29
	v_cvt_pk_bf16_f32 v23, v30, v31
	s_nop 1
	v_permlane32_swap_b32_e32 v16, v18
	v_permlane32_swap_b32_e32 v17, v19
	v_permlane32_swap_b32_e32 v20, v22
	v_permlane32_swap_b32_e32 v21, v23
	global_store_dwordx4 v[254:255], v[16:19], off offset:192
	global_store_dwordx4 v[254:255], v[20:23], off offset:224
	s_waitcnt lgkmcnt(0)
	s_barrier
	s_add_i32 s15, s15, s34
	s_cmp_lt_i32 s15, s14
	s_cbranch_scc0 .LBB0_729
	s_branch .LBB0_551
